# MLA up-projection GEMM tile stores write-through; leader write-back also skipped after the MLA GEMM phase
# baseline (speedup 1.0000x reference)
.Lxb_leader:
	v_readlane_b32 s98, v252, 2
	s_nop 0
	s_sub_i32 s98, s98, 4
	s_cmp_lt_i32 s98, 0
	s_cbranch_scc1 .Lxb_flush
	s_mul_i32 s99, s98, 0x1746
	s_lshr_b32 s99, s99, 16
	s_mul_i32 s99, s99, 11
	s_sub_i32 s98, s98, s99
	s_lshl_b32 s98, 1, s98
	s_and_b32 s98, s98, 0x6e4
	s_cmp_lg_u32 s98, 0
	s_cbranch_scc1 .Lxb_noflush
